# attention k-loop: software-pipelined K/V LDS fragment reads (4 buffers, counted lgkmcnt), V prefetch at QK tail, TMAX load hoisted
# speedup vs baseline: 1.0246x; 1.0246x over previous
; #define MFMA16(a, b, c) __builtin_amdgcn_mfma_f32_16x16x32_bf16((a), (b), (c), 0, 0, 0)
;     ...
;         for (int kt = 0; kt < nkt; ++kt) {
;             const bool more = kt + 1 < nkt;
;             if (more) issue(kt + 1, (kt + 1) & 1);
;             const char* sb = smem + (kt & 1) * AT_STAGE;
;             if (kt * 64 < q1w) {
;             f32x4 as[4][2];
; #pragma unroll
;             for (int kb = 0; kb < 4; ++kb)
; #pragma unroll
;                 for (int qb = 0; qb < 2; ++qb) as[kb][qb] = (f32x4){0.f, 0.f, 0.f, 0.f};
; #pragma unroll
;             for (int ds = 0; ds < 6; ++ds) {
;                 const int ch = 4 * ds + qq;
; #pragma unroll
;                 for (int kb = 0; kb < 4; ++kb) {
;                     const int krow = krow0 + 32 * (kb >> 1) + 4 * (kb & 1), key = kkey;
;                     const bf16x8 kf = *(const bf16x8*)(sb + krow * 384 + (((ch & 24) | ((ch ^ key) & 7)) << 4));
; #pragma unroll
;                     for (int qb = 0; qb < 2; ++qb) as[kb][qb] = MFMA16(kf, qf[ds][qb], as[kb][qb]);
;                 }
;             }
;             const bool need_mask = (kt >= 4 * qt) || (TMAX[((gtb) >> 6) + kt] > tminq);
.LBB0_931:
	s_add_u32 s100, s22, s90
	s_addc_u32 s101, s23, s91
	global_load_dword v251, v177, s[100:101]
	s_add_i32 s88, s0, 1
	s_bitcmp1_b32 s88, 0
	s_cselect_b32 s1, 0xa000, 0
	s_add_i32 s19, s1, 16
	v_add_u32_e32 v112, s19, v186
	v_add_u32_e32 v113, 0x400, v112
	v_readfirstlane_b32 s1, v112
	s_mov_b32 m0, s1
	v_readfirstlane_b32 s1, v113
	v_add_u32_e32 v112, 0x800, v112
	global_load_lds_dwordx4 v235, s[22:23]
	s_mov_b32 m0, s1
	v_readfirstlane_b32 s1, v112
	v_add_u32_e32 v112, s19, v187
	v_add_u32_e32 v113, 0x6000, v112
	global_load_lds_dwordx4 v234, s[22:23]
	s_mov_b32 m0, s1
	v_readfirstlane_b32 s1, v113
	v_add_u32_e32 v112, 0x6400, v112
	global_load_lds_dwordx4 v233, s[22:23]
	s_mov_b32 m0, s1
	v_readfirstlane_b32 s1, v112
	global_load_lds_dwordx4 v232, s[22:23]
	s_mov_b32 m0, s1
	v_cmp_lt_i32_e32 vcc, s92, v222
	global_load_lds_dwordx4 v231, s[22:23]
	s_and_saveexec_b64 s[26:27], vcc
	s_cbranch_execz .LBB0_939
	s_bitcmp1_b32 s0, 0
	s_cselect_b32 s1, 0xa000, 0
	s_add_i32 s93, s1, 16
	v_add3_u32 v148, s93, v198, v199
	v_add3_u32 v152, s93, v200, v199
	ds_read_b128 v[144:147], v148
	ds_read_b128 v[236:239], v148 offset:1536
	ds_read_b128 v[240:243], v148 offset:12288
	ds_read_b128 v[244:247], v148 offset:13824
	s_cmp_ge_u32 s0, s35
	s_cselect_b64 s[0:1], -1, 0
	s_and_b64 vcc, exec, s[0:1]
	v_add3_u32 v248, s93, v188, v201
	v_add3_u32 v250, s93, v188, v202
	s_waitcnt lgkmcnt(3)
	v_mfma_f32_16x16x32_bf16 v[128:131], v[144:147], v[104:107], 0
	v_mfma_f32_16x16x32_bf16 v[116:119], v[144:147], v[108:111], 0
	ds_read_b128 v[144:147], v152
	s_waitcnt lgkmcnt(3)
	v_mfma_f32_16x16x32_bf16 v[124:127], v[236:239], v[104:107], 0
	v_mfma_f32_16x16x32_bf16 v[112:115], v[236:239], v[108:111], 0
	ds_read_b128 v[236:239], v152 offset:1536
	s_waitcnt lgkmcnt(3)
	v_mfma_f32_16x16x32_bf16 v[132:135], v[240:243], v[104:107], 0
	v_mfma_f32_16x16x32_bf16 v[120:123], v[240:243], v[108:111], 0
	ds_read_b128 v[240:243], v152 offset:12288
	s_waitcnt lgkmcnt(3)
	v_mfma_f32_16x16x32_bf16 v[140:143], v[244:247], v[104:107], 0
	v_mfma_f32_16x16x32_bf16 v[136:139], v[244:247], v[108:111], 0
	ds_read_b128 v[244:247], v152 offset:13824
	s_waitcnt lgkmcnt(3)
	v_mfma_f32_16x16x32_bf16 v[128:131], v[144:147], v[96:99], v[128:131]
	v_mfma_f32_16x16x32_bf16 v[116:119], v[144:147], v[100:103], v[116:119]
	ds_read_b128 v[144:147], v148 offset:128
	s_waitcnt lgkmcnt(3)
	v_mfma_f32_16x16x32_bf16 v[124:127], v[236:239], v[96:99], v[124:127]
	v_mfma_f32_16x16x32_bf16 v[112:115], v[236:239], v[100:103], v[112:115]
	ds_read_b128 v[236:239], v148 offset:1664
	s_waitcnt lgkmcnt(3)
	v_mfma_f32_16x16x32_bf16 v[132:135], v[240:243], v[96:99], v[132:135]
	v_mfma_f32_16x16x32_bf16 v[120:123], v[240:243], v[100:103], v[120:123]
	ds_read_b128 v[240:243], v148 offset:12416
	s_waitcnt lgkmcnt(3)
	v_mfma_f32_16x16x32_bf16 v[140:143], v[244:247], v[96:99], v[140:143]
	v_mfma_f32_16x16x32_bf16 v[136:139], v[244:247], v[100:103], v[136:139]
	ds_read_b128 v[244:247], v148 offset:13952
	s_waitcnt lgkmcnt(3)
	v_mfma_f32_16x16x32_bf16 v[128:131], v[144:147], v[88:91], v[128:131]
	v_mfma_f32_16x16x32_bf16 v[116:119], v[144:147], v[92:95], v[116:119]
	ds_read_b128 v[144:147], v152 offset:128
	s_waitcnt lgkmcnt(3)
	v_mfma_f32_16x16x32_bf16 v[124:127], v[236:239], v[88:91], v[124:127]
	v_mfma_f32_16x16x32_bf16 v[112:115], v[236:239], v[92:95], v[112:115]
	ds_read_b128 v[236:239], v152 offset:1664
	s_waitcnt lgkmcnt(3)
	v_mfma_f32_16x16x32_bf16 v[132:135], v[240:243], v[88:91], v[132:135]
	v_mfma_f32_16x16x32_bf16 v[120:123], v[240:243], v[92:95], v[120:123]
	ds_read_b128 v[240:243], v152 offset:12416
	s_waitcnt lgkmcnt(3)
	v_mfma_f32_16x16x32_bf16 v[140:143], v[244:247], v[88:91], v[140:143]
	v_mfma_f32_16x16x32_bf16 v[136:139], v[244:247], v[92:95], v[136:139]
	ds_read_b128 v[244:247], v152 offset:13952
	s_waitcnt lgkmcnt(3)
	v_mfma_f32_16x16x32_bf16 v[128:131], v[144:147], v[80:83], v[128:131]
	v_mfma_f32_16x16x32_bf16 v[116:119], v[144:147], v[84:87], v[116:119]
	ds_read_b128 v[144:147], v148 offset:256
	s_waitcnt lgkmcnt(3)
	v_mfma_f32_16x16x32_bf16 v[124:127], v[236:239], v[80:83], v[124:127]
	v_mfma_f32_16x16x32_bf16 v[112:115], v[236:239], v[84:87], v[112:115]
	ds_read_b128 v[236:239], v148 offset:1792
	s_waitcnt lgkmcnt(3)
	v_mfma_f32_16x16x32_bf16 v[132:135], v[240:243], v[80:83], v[132:135]
	v_mfma_f32_16x16x32_bf16 v[120:123], v[240:243], v[84:87], v[120:123]
	ds_read_b128 v[240:243], v148 offset:12544
	s_waitcnt lgkmcnt(3)
	v_mfma_f32_16x16x32_bf16 v[140:143], v[244:247], v[80:83], v[140:143]
	v_mfma_f32_16x16x32_bf16 v[136:139], v[244:247], v[84:87], v[136:139]
	ds_read_b128 v[244:247], v148 offset:14080
	s_waitcnt lgkmcnt(3)
	v_mfma_f32_16x16x32_bf16 v[128:131], v[144:147], v[72:75], v[128:131]
	v_mfma_f32_16x16x32_bf16 v[116:119], v[144:147], v[76:79], v[116:119]
	ds_read_b128 v[144:147], v152 offset:256
	s_waitcnt lgkmcnt(3)
	v_mfma_f32_16x16x32_bf16 v[124:127], v[236:239], v[72:75], v[124:127]
	v_mfma_f32_16x16x32_bf16 v[112:115], v[236:239], v[76:79], v[112:115]
	ds_read_b128 v[236:239], v152 offset:1792
	s_waitcnt lgkmcnt(3)
	v_mfma_f32_16x16x32_bf16 v[132:135], v[240:243], v[72:75], v[132:135]
	v_mfma_f32_16x16x32_bf16 v[120:123], v[240:243], v[76:79], v[120:123]
	ds_read_b128 v[240:243], v152 offset:12544
	s_waitcnt lgkmcnt(3)
	v_mfma_f32_16x16x32_bf16 v[140:143], v[244:247], v[72:75], v[140:143]
	v_mfma_f32_16x16x32_bf16 v[136:139], v[244:247], v[76:79], v[136:139]
	ds_read_b128 v[244:247], v152 offset:14080
	s_waitcnt lgkmcnt(3)
	v_mfma_f32_16x16x32_bf16 v[128:131], v[144:147], v[64:67], v[128:131]
	v_mfma_f32_16x16x32_bf16 v[116:119], v[144:147], v[68:71], v[116:119]
	s_waitcnt lgkmcnt(2)
	v_mfma_f32_16x16x32_bf16 v[124:127], v[236:239], v[64:67], v[124:127]
	v_mfma_f32_16x16x32_bf16 v[112:115], v[236:239], v[68:71], v[112:115]
	ds_read_b128 v[236:239], v248 offset:24576
	s_waitcnt lgkmcnt(2)
	v_mfma_f32_16x16x32_bf16 v[132:135], v[240:243], v[64:67], v[132:135]
	v_mfma_f32_16x16x32_bf16 v[120:123], v[240:243], v[68:71], v[120:123]
	ds_read_b128 v[240:243], v248 offset:26624
	s_waitcnt lgkmcnt(2)
	v_mfma_f32_16x16x32_bf16 v[140:143], v[244:247], v[64:67], v[140:143]
	v_mfma_f32_16x16x32_bf16 v[136:139], v[244:247], v[68:71], v[136:139]
	ds_read_b128 v[244:247], v248 offset:28672
	s_cbranch_vccnz .LBB0_934
	s_waitcnt vmcnt(5)
	v_cmp_gt_i32_e64 s[0:1], v251, v223

; #define MFMA16(a, b, c) __builtin_amdgcn_mfma_f32_16x16x32_bf16((a), (b), (c), 0, 0, 0)
; DI unsigned pk2(float lo, float hi) { f32x2 v = {lo, hi}; return __builtin_bit_cast(unsigned, __builtin_convertvector(v, bf16x2_t)); }
; DI float fexp2(float x) { return __builtin_amdgcn_exp2f(x); }
;     ...
;             float alpha[2];
; #pragma unroll
;             for (int qb = 0; qb < 2; ++qb) {
;                 float mx = as[0][qb][0];
; #pragma unroll
;                 for (int kb = 0; kb < 4; ++kb)
; #pragma unroll
;                     for (int rr = 0; rr < 4; ++rr) mx = fmaxf(mx, as[kb][qb][rr]);
;                 mx = fmaxf(mx, __shfl_xor(mx, 16)); mx = fmaxf(mx, __shfl_xor(mx, 32));
;                 const float mnew = fmaxf(m[qb], mx);
;                 alpha[qb] = fexp2(m[qb] - mnew); m[qb] = mnew;
;                 float ps = 0.f;
; #pragma unroll
;                 for (int kb = 0; kb < 4; ++kb)
; #pragma unroll
;                     for (int rr = 0; rr < 4; ++rr) { const float pv = fexp2(as[kb][qb][rr] - mnew); as[kb][qb][rr] = pv; ps += pv; }
;                 lsum[qb] = lsum[qb] * alpha[qb] + ps;
;             }
;             if (__builtin_amdgcn_ballot_w64(alpha[0] != 1.f || alpha[1] != 1.f) != 0ull) {
; #pragma unroll
;                 for (int d = 0; d < 8; ++d)
; #pragma unroll
;                     for (int qb = 0; qb < 2; ++qb) ao[d][qb] = ao[d][qb] * alpha[qb];
;             }
;             bf16x8 pf[2][2];
; #pragma unroll
;             for (int k2 = 0; k2 < 2; ++k2)
; #pragma unroll
;                 for (int qb = 0; qb < 2; ++qb) {
;                     u32x4 pkd;
;                     pkd.x = pk2(as[2 * k2][qb][0], as[2 * k2][qb][1]); pkd.y = pk2(as[2 * k2][qb][2], as[2 * k2][qb][3]);
;                     pkd.z = pk2(as[2 * k2 + 1][qb][0], as[2 * k2 + 1][qb][1]); pkd.w = pk2(as[2 * k2 + 1][qb][2], as[2 * k2 + 1][qb][3]);
;                     pf[k2][qb] = __builtin_bit_cast(bf16x8, pkd);
;                 }
; #pragma unroll
;             for (int k2 = 0; k2 < 2; ++k2) {
;                 const int ph = ((4 * k2 + qq) ^ vkey) << 4;
; #pragma unroll
;                 for (int d = 0; d < 8; ++d) {
;                     const bf16x8 vf = *(const bf16x8*)(sb + AT_KB + (d * 16 + r16) * 128 + ph);
; #pragma unroll
;                     for (int qb = 0; qb < 2; ++qb) ao[d][qb] = MFMA16(vf, pf[k2][qb], ao[d][qb]);
;                 }
;             }
.LBB0_938:
	v_sub_f32_e32 v129, v129, v146
	v_exp_f32_e32 v148, v129
	v_sub_f32_e32 v129, v130, v146
	v_sub_f32_e32 v128, v128, v146
	v_exp_f32_e32 v130, v129
	v_sub_f32_e32 v129, v131, v146
	v_sub_f32_e32 v124, v124, v146
	v_sub_f32_e32 v116, v116, v147
	v_sub_f32_e32 v112, v112, v147
	v_exp_f32_e32 v128, v128
	v_exp_f32_e32 v150, v129
	v_exp_f32_e32 v152, v124
	v_sub_f32_e32 v124, v125, v146
	v_exp_f32_e32 v129, v116
	v_sub_f32_e32 v116, v117, v147
	v_exp_f32_e32 v153, v112
	v_sub_f32_e32 v112, v113, v147
	v_exp_f32_e32 v154, v124
	v_sub_f32_e32 v124, v126, v146
	v_exp_f32_e32 v149, v116
	v_sub_f32_e32 v116, v118, v147
	v_exp_f32_e32 v155, v112
	v_sub_f32_e32 v112, v114, v147
	v_exp_f32_e32 v126, v124
	v_sub_f32_e32 v124, v127, v146
	v_exp_f32_e32 v131, v116
	v_sub_f32_e32 v116, v119, v147
	v_exp_f32_e32 v127, v112
	v_sub_f32_e32 v112, v115, v147
	v_exp_f32_e32 v156, v124
	v_sub_f32_e32 v124, v132, v146
	v_exp_f32_e32 v151, v116
	v_exp_f32_e32 v157, v112
	v_sub_f32_e32 v112, v120, v147
	v_exp_f32_e32 v132, v124
	v_sub_f32_e32 v124, v133, v146
	v_exp_f32_e32 v133, v112
	v_pk_add_f32 v[112:113], v[128:129], 0 op_sel_hi:[1,0]
	v_sub_f32_e32 v114, v121, v147
	v_pk_add_f32 v[112:113], v[148:149], v[112:113]
	v_exp_f32_e32 v158, v124
	v_pk_add_f32 v[112:113], v[130:131], v[112:113]
	v_sub_f32_e32 v124, v134, v146
	v_pk_add_f32 v[112:113], v[150:151], v[112:113]
	v_exp_f32_e32 v159, v114
	v_pk_add_f32 v[112:113], v[152:153], v[112:113]
	v_sub_f32_e32 v114, v122, v147
	v_pk_add_f32 v[112:113], v[154:155], v[112:113]
	v_exp_f32_e32 v134, v124
	v_sub_f32_e32 v124, v135, v146
	v_pk_add_f32 v[112:113], v[126:127], v[112:113]
	v_exp_f32_e32 v135, v114
	v_sub_f32_e32 v114, v123, v147
	v_exp_f32_e32 v208, v124
	v_sub_f32_e32 v124, v140, v146
	v_pk_add_f32 v[112:113], v[156:157], v[112:113]
	v_exp_f32_e32 v209, v114
	v_sub_f32_e32 v114, v136, v147
	v_exp_f32_e32 v140, v124
	v_sub_f32_e32 v124, v141, v146
	v_pk_add_f32 v[112:113], v[132:133], v[112:113]
	v_exp_f32_e32 v141, v114
	v_sub_f32_e32 v114, v137, v147
	v_exp_f32_e32 v214, v124
	v_sub_f32_e32 v124, v142, v146
	v_exp_f32_e32 v215, v114
	v_sub_f32_e32 v114, v138, v147
	v_pk_add_f32 v[112:113], v[158:159], v[112:113]
	v_exp_f32_e32 v142, v124
	v_sub_f32_e32 v124, v143, v146
	v_exp_f32_e32 v143, v114
	v_sub_f32_e32 v114, v139, v147
	v_pk_add_f32 v[112:113], v[134:135], v[112:113]
	v_exp_f32_e32 v220, v124
	v_exp_f32_e32 v221, v114
	v_pk_add_f32 v[112:113], v[208:209], v[112:113]
	v_cvt_pk_bf16_f32 v116, v132, v158
	v_pk_add_f32 v[112:113], v[140:141], v[112:113]
	v_pk_add_f32 v[112:113], v[214:215], v[112:113]
	v_cvt_pk_bf16_f32 v120, v128, v148
	v_pk_add_f32 v[112:113], v[142:143], v[112:113]
	v_cvt_pk_bf16_f32 v121, v130, v150
	v_pk_add_f32 v[112:113], v[220:221], v[112:113]
	v_cvt_pk_bf16_f32 v124, v129, v149
	v_pk_fma_f32 v[172:173], v[172:173], v[144:145], v[112:113]
	v_cvt_pk_bf16_f32 v112, v133, v159
	v_cvt_pk_bf16_f32 v125, v131, v151
	ds_read_b128 v[128:131], v248 offset:30720
	v_cvt_pk_bf16_f32 v122, v152, v154
	v_cvt_pk_bf16_f32 v123, v126, v156
	v_cvt_pk_bf16_f32 v126, v153, v155
	v_cvt_pk_bf16_f32 v127, v127, v157
	s_waitcnt lgkmcnt(3)
	v_mfma_f32_16x16x32_bf16 v[56:59], v[236:239], v[120:123], v[56:59]
	v_cvt_pk_bf16_f32 v117, v134, v208
	v_cvt_pk_bf16_f32 v118, v140, v214
	v_cvt_pk_bf16_f32 v119, v142, v220
	v_mfma_f32_16x16x32_bf16 v[44:47], v[236:239], v[124:127], v[44:47]
	ds_read_b128 v[236:239], v248 offset:32768
	v_cvt_pk_bf16_f32 v113, v135, v209
	v_cvt_pk_bf16_f32 v114, v141, v215
	s_waitcnt lgkmcnt(3)
	v_mfma_f32_16x16x32_bf16 v[60:63], v[240:243], v[120:123], v[60:63]
	v_cvt_pk_bf16_f32 v115, v143, v221
	v_mov_b32_e32 v224, v147
	v_mov_b32_e32 v225, v146
	v_mfma_f32_16x16x32_bf16 v[48:51], v[240:243], v[124:127], v[48:51]
	ds_read_b128 v[240:243], v248 offset:34816
	s_waitcnt lgkmcnt(3)
	v_mfma_f32_16x16x32_bf16 v[52:55], v[244:247], v[120:123], v[52:55]
	v_mfma_f32_16x16x32_bf16 v[36:39], v[244:247], v[124:127], v[36:39]
	ds_read_b128 v[244:247], v248 offset:36864
	s_waitcnt lgkmcnt(3)
	v_mfma_f32_16x16x32_bf16 v[40:43], v[128:131], v[120:123], v[40:43]
	v_mfma_f32_16x16x32_bf16 v[28:31], v[128:131], v[124:127], v[28:31]
	ds_read_b128 v[128:131], v248 offset:38912
	s_waitcnt lgkmcnt(3)
	v_mfma_f32_16x16x32_bf16 v[32:35], v[236:239], v[120:123], v[32:35]
	v_mfma_f32_16x16x32_bf16 v[16:19], v[236:239], v[124:127], v[16:19]
	ds_read_b128 v[236:239], v250 offset:24576
	s_waitcnt lgkmcnt(3)
	v_mfma_f32_16x16x32_bf16 v[20:23], v[240:243], v[120:123], v[20:23]
	v_mfma_f32_16x16x32_bf16 v[0:3], v[240:243], v[124:127], v[0:3]
	ds_read_b128 v[240:243], v250 offset:26624
	s_waitcnt lgkmcnt(3)
	v_mfma_f32_16x16x32_bf16 v[8:11], v[244:247], v[120:123], v[8:11]
	v_mfma_f32_16x16x32_bf16 v[4:7], v[244:247], v[124:127], v[4:7]
	ds_read_b128 v[244:247], v250 offset:28672
	s_waitcnt lgkmcnt(3)
	v_mfma_f32_16x16x32_bf16 v[24:27], v[128:131], v[120:123], v[24:27]
	v_mfma_f32_16x16x32_bf16 v[12:15], v[128:131], v[124:127], v[12:15]
	ds_read_b128 v[128:131], v250 offset:30720
	s_waitcnt lgkmcnt(3)
	v_mfma_f32_16x16x32_bf16 v[56:59], v[236:239], v[116:119], v[56:59]
	v_mfma_f32_16x16x32_bf16 v[44:47], v[236:239], v[112:115], v[44:47]
	ds_read_b128 v[236:239], v250 offset:32768
	s_waitcnt lgkmcnt(3)
	v_mfma_f32_16x16x32_bf16 v[60:63], v[240:243], v[116:119], v[60:63]
	v_mfma_f32_16x16x32_bf16 v[48:51], v[240:243], v[112:115], v[48:51]
	ds_read_b128 v[240:243], v250 offset:34816
	s_waitcnt lgkmcnt(3)
	v_mfma_f32_16x16x32_bf16 v[52:55], v[244:247], v[116:119], v[52:55]
	v_mfma_f32_16x16x32_bf16 v[36:39], v[244:247], v[112:115], v[36:39]
	ds_read_b128 v[244:247], v250 offset:36864
	s_waitcnt lgkmcnt(3)
	v_mfma_f32_16x16x32_bf16 v[40:43], v[128:131], v[116:119], v[40:43]
	v_mfma_f32_16x16x32_bf16 v[28:31], v[128:131], v[112:115], v[28:31]
	ds_read_b128 v[128:131], v250 offset:38912
	s_waitcnt lgkmcnt(3)
	v_mfma_f32_16x16x32_bf16 v[32:35], v[236:239], v[116:119], v[32:35]
	v_mfma_f32_16x16x32_bf16 v[16:19], v[236:239], v[112:115], v[16:19]
	s_waitcnt lgkmcnt(2)
	v_mfma_f32_16x16x32_bf16 v[20:23], v[240:243], v[116:119], v[20:23]
	v_mfma_f32_16x16x32_bf16 v[0:3], v[240:243], v[112:115], v[0:3]
	s_waitcnt lgkmcnt(1)
	v_mfma_f32_16x16x32_bf16 v[8:11], v[244:247], v[116:119], v[8:11]
	v_mfma_f32_16x16x32_bf16 v[4:7], v[244:247], v[112:115], v[4:7]
	s_waitcnt lgkmcnt(0)
	v_mfma_f32_16x16x32_bf16 v[24:27], v[128:131], v[116:119], v[24:27]
	v_mfma_f32_16x16x32_bf16 v[12:15], v[128:131], v[112:115], v[12:15]

; __global__ void __launch_bounds__(NTH) mega(Params P) {
	.amdhsa_kernel _Z4mega6Params
		.amdhsa_group_segment_fixed_size 16
		.amdhsa_private_segment_fixed_size 0
		.amdhsa_kernarg_size 752
		.amdhsa_user_sgpr_count 2
		.amdhsa_user_sgpr_dispatch_ptr 0
		.amdhsa_user_sgpr_queue_ptr 0
		.amdhsa_user_sgpr_kernarg_segment_ptr 1
		.amdhsa_user_sgpr_dispatch_id 0
		.amdhsa_user_sgpr_kernarg_preload_length 0
		.amdhsa_user_sgpr_kernarg_preload_offset 0
		.amdhsa_user_sgpr_private_segment_size 0
		.amdhsa_uses_dynamic_stack 0
		.amdhsa_enable_private_segment 0
		.amdhsa_system_sgpr_workgroup_id_x 1
		.amdhsa_system_sgpr_workgroup_id_y 0
		.amdhsa_system_sgpr_workgroup_id_z 0
		.amdhsa_system_sgpr_workgroup_info 0
		.amdhsa_system_vgpr_workitem_id 2
		.amdhsa_next_free_vgpr 256
		.amdhsa_next_free_sgpr 102
		.amdhsa_accum_offset 256
		.amdhsa_reserve_vcc 1
		.amdhsa_float_round_mode_32 0
		.amdhsa_float_round_mode_16_64 0
		.amdhsa_float_denorm_mode_32 3
		.amdhsa_float_denorm_mode_16_64 3
		.amdhsa_dx10_clamp 1
		.amdhsa_ieee_mode 1
		.amdhsa_fp16_overflow 0
		.amdhsa_tg_split 0
		.amdhsa_exception_fp_ieee_invalid_op 0
		.amdhsa_exception_fp_denorm_src 0
		.amdhsa_exception_fp_ieee_div_zero 0
		.amdhsa_exception_fp_ieee_overflow 0
		.amdhsa_exception_fp_ieee_underflow 0
		.amdhsa_exception_fp_ieee_inexact 0
		.amdhsa_exception_int_div_zero 0
	.end_amdhsa_kernel

; __global__ void __launch_bounds__(NTH) mega(Params P) {
amdhsa.kernels:
  - .agpr_count:     0
    .args:
      - .offset:         0
        .size:           496
        .value_kind:     by_value
      - .offset:         496
        .size:           4
        .value_kind:     hidden_block_count_x
      - .offset:         500
        .size:           4
        .value_kind:     hidden_block_count_y
      - .offset:         504
        .size:           4
        .value_kind:     hidden_block_count_z
      - .offset:         508
        .size:           2
        .value_kind:     hidden_group_size_x
      - .offset:         510
        .size:           2
        .value_kind:     hidden_group_size_y
      - .offset:         512
        .size:           2
        .value_kind:     hidden_group_size_z
      - .offset:         514
        .size:           2
        .value_kind:     hidden_remainder_x
      - .offset:         516
        .size:           2
        .value_kind:     hidden_remainder_y
      - .offset:         518
        .size:           2
        .value_kind:     hidden_remainder_z
      - .offset:         536
        .size:           8
        .value_kind:     hidden_global_offset_x
      - .offset:         544
        .size:           8
        .value_kind:     hidden_global_offset_y
      - .offset:         552
        .size:           8
        .value_kind:     hidden_global_offset_z
      - .offset:         560
        .size:           2
        .value_kind:     hidden_grid_dims
      - .offset:         584
        .size:           8
        .value_kind:     hidden_multigrid_sync_arg
      - .offset:         616
        .size:           4
        .value_kind:     hidden_dynamic_lds_size
    .group_segment_fixed_size: 16
    .kernarg_segment_align: 8
    .kernarg_segment_size: 752
    .language:       OpenCL C
    .language_version:
      - 2
      - 0
    .max_flat_workgroup_size: 512
    .name:           _Z4mega6Params
    .private_segment_fixed_size: 0
    .sgpr_count:     108
    .sgpr_spill_count: 191
    .symbol:         _Z4mega6Params.kd
    .uniform_work_group_size: 1
    .uses_dynamic_stack: false
    .vgpr_count:     256
    .vgpr_spill_count: 0
    .wavefront_size: 64
